# down-projection and w_out GEMM epilogues: residual / gate loads batched and issued a group ahead into spare registers, counted waits
# baseline (speedup 1.0000x reference)
;     __device__ __forceinline__ void operator()(const f32x4 (&acc)[2][2][4][2], const pg8::Unit& u, int wr, int wc, int fr, int fq) const {
;     ...
;                     } else if constexpr (MODE == 7) {
;                         const f32x4 g0 = *(const f32x4*)(vec + col), g1 = *(const f32x4*)(vec + col + 4);
;                         const f32x4 x0 = *(const f32x4*)(xsrc + row * DM + col), x1 = *(const f32x4*)(xsrc + row * DM + col + 4);
;                         const f32x4 y0 = x0 + g0 * v0, y1 = x1 + g1 * v1;
;                         *(f32x4*)(of + row * DM + col) = y0; *(f32x4*)(of + row * DM + col + 4) = y1;
;                         ssq += (y0[0] * y0[0] + y0[1] * y0[1]) + (y0[2] * y0[2] + y0[3] * y0[3]) + (y1[0] * y1[0] + y1[1] * y1[1]) + (y1[2] * y1[2] + y1[3] * y1[3]);
;                         const f32x4 s0 = *(const f32x4*)(vec2 + col) + 1.f, s1 = *(const f32x4*)(vec2 + col + 4) + 1.f;
;                         const f32x4 a0 = y0 * s0, a1 = y1 * s1;
;                         u32x4 w; w.x = pk2(a0[0], a0[1]); w.y = pk2(a0[2], a0[3]); w.z = pk2(a1[0], a1[1]); w.w = pk2(a1[2], a1[3]);
;                         *(u32x4*)(ob + row * DM + col) = w;
;                     } else if constexpr (MODE == 8) {
;                         const f32x4 b0 = *(const f32x4*)(vec + col), b1 = *(const f32x4*)(vec + col + 4);
;                         float r[8] = {v0[0] * rstd + b0[0], v0[1] * rstd + b0[1], v0[2] * rstd + b0[2], v0[3] * rstd + b0[3], v1[0] * rstd + b1[0], v1[1] * rstd + b1[1], v1[2] * rstd + b1[2], v1[3] * rstd + b1[3]};
; #pragma unroll
;                         for (int i = 0; i < 8; ++i) { const float q = fmaxf(r[i], 0.f); r[i] = q * q; }
;                         u32x4 w; w.x = pk2(r[0], r[1]); w.y = pk2(r[2], r[3]); w.z = pk2(r[4], r[5]); w.w = pk2(r[6], r[7]);
;                         *(u32x4*)(ob + row * HIDN + col) = w;
;                     } else {
;                         float r[8] = {v0[0], v0[1], v0[2], v0[3], v1[0], v1[1], v1[2], v1[3]};
; #pragma unroll
;                         for (int i = 0; i < 8; ++i) { const float q = fmaxf(r[i], 0.f); r[i] = q * q; }
;                         u32x4 w; w.x = pk2(r[0], r[1]); w.y = pk2(r[2], r[3]); w.z = pk2(r[4], r[5]); w.w = pk2(r[6], r[7]);
;                         *(u32x4*)(ob + row * HIDN + col) = w;
;                     }
;                 }
;                 if constexpr (MODE == 7) {
.LBB0_62:
	v_lshl_add_u32 v144, s10, 8, v150
	v_lshl_or_b32 v138, s16, 8, v152
	v_ashrrev_i32_e32 v145, 31, v144
	v_ashrrev_i32_e32 v139, 31, v138
	v_lshlrev_b64 v[148:149], 13, v[144:145]
	v_lshlrev_b64 v[140:141], 2, v[138:139]
	v_lshl_add_u64 v[146:147], s[30:31], 0, v[148:149]
	v_lshl_add_u64 v[142:143], s[4:5], 0, v[140:141]
	v_lshl_add_u64 v[146:147], v[146:147], 0, v[140:141]
	global_load_dwordx4 v[196:199], v[142:143], off offset:16
	global_load_dwordx4 v[200:203], v[142:143], off
	global_load_dwordx4 v[214:217], v[146:147], off offset:16
	global_load_dwordx4 v[218:221], v[146:147], off
	v_lshl_add_u64 v[230:231], s[42:43], 0, v[140:141]
	global_load_dwordx4 v[222:225], v[230:231], off offset:16
	global_load_dwordx4 v[226:229], v[230:231], off
	v_readlane_b32 s28, v251, 7
	v_readlane_b32 s29, v251, 8
	s_waitcnt vmcnt(0)
	v_pk_fma_f32 v[186:187], v[126:127], v[202:203], v[220:221]
	v_pk_fma_f32 v[184:185], v[124:125], v[200:201], v[218:219]
	v_pk_fma_f32 v[124:125], v[122:123], v[198:199], v[216:217]
	v_pk_fma_f32 v[122:123], v[120:121], v[196:197], v[214:215]
	v_lshl_add_u64 v[120:121], s[6:7], 0, v[148:149]
	v_lshl_add_u64 v[126:127], v[120:121], 0, v[140:141]
	v_mul_f32_e32 v120, v185, v185
	v_mul_f32_e32 v121, v187, v187
	v_fmac_f32_e32 v120, v184, v184
	v_fmac_f32_e32 v121, v186, v186
	v_add_f32_e32 v120, v120, v121
	v_mul_f32_e32 v121, v123, v123
	v_fmac_f32_e32 v121, v122, v122
	v_add_f32_e32 v120, v120, v121
	v_mul_f32_e32 v121, v125, v125
	v_fmac_f32_e32 v121, v124, v124
	global_store_dwordx4 v[126:127], v[184:187], off
	global_store_dwordx4 v[126:127], v[122:125], off offset:16
	v_add_f32_e32 v162, v121, v120
	v_lshl_add_u64 v[120:121], s[42:43], 0, v[140:141]
	v_pk_add_f32 v[154:155], v[222:223], 1.0 op_sel_hi:[1,0]
	v_pk_add_f32 v[158:159], v[226:227], 1.0 op_sel_hi:[1,0]
	v_pk_mul_f32 v[122:123], v[122:123], v[154:155]
	v_pk_mul_f32 v[158:159], v[184:185], v[158:159]
	v_pk_add_f32 v[148:149], v[228:229], 1.0 op_sel_hi:[1,0]
	v_pk_mul_f32 v[148:149], v[186:187], v[148:149]
	v_cvt_pk_bf16_f32 v154, v158, v159
	v_cvt_pk_bf16_f32 v155, v148, v149
	v_pk_add_f32 v[156:157], v[224:225], 1.0 op_sel_hi:[1,0]
	v_pk_mul_f32 v[124:125], v[124:125], v[156:157]
	v_cvt_pk_bf16_f32 v156, v122, v123
	v_cvt_pk_bf16_f32 v157, v124, v125
	v_lshlrev_b64 v[122:123], 12, v[144:145]
	v_lshl_add_u64 v[122:123], s[28:29], 0, v[122:123]
	v_lshl_add_u64 v[124:125], v[138:139], 1, v[122:123]
	v_or_b32_e32 v122, 0x80, v138
	v_ashrrev_i32_e32 v123, 31, v122
	v_lshlrev_b64 v[148:149], 2, v[122:123]
	global_store_dwordx4 v[124:125], v[154:157], off
	v_lshl_add_u64 v[122:123], s[4:5], 0, v[148:149]
	v_or_b32_e32 v230, 0x80, v138
	v_ashrrev_i32_e32 v231, 31, v230
	v_lshlrev_b64 v[232:233], 2, v[230:231]
	v_lshl_add_u64 v[230:231], s[4:5], 0, v[232:233]
	global_load_dwordx4 v[196:199], v[230:231], off offset:16
	global_load_dwordx4 v[200:203], v[230:231], off
	global_load_dwordx4 v[214:217], v[146:147], off offset:528
	global_load_dwordx4 v[218:221], v[146:147], off offset:512
	v_or_b32_e32 v230, 0x80, v138
	v_ashrrev_i32_e32 v231, 31, v230
	v_lshlrev_b64 v[232:233], 2, v[230:231]
	v_lshl_add_u64 v[234:235], s[42:43], 0, v[232:233]
	global_load_dwordx4 v[222:225], v[234:235], off offset:16
	global_load_dwordx4 v[226:229], v[234:235], off
	s_waitcnt vmcnt(0)
	v_pk_fma_f32 v[154:155], v[112:113], v[196:197], v[214:215]
	v_pk_fma_f32 v[118:119], v[118:119], v[202:203], v[220:221]
	v_pk_fma_f32 v[116:117], v[116:117], v[200:201], v[218:219]
	v_mul_f32_e32 v113, v119, v119
	v_mul_f32_e32 v112, v117, v117
	v_fmac_f32_e32 v112, v116, v116
	v_fmac_f32_e32 v113, v118, v118
	v_add_f32_e32 v112, v112, v113
	v_mul_f32_e32 v113, v155, v155
	v_pk_fma_f32 v[156:157], v[114:115], v[198:199], v[216:217]
	v_fmac_f32_e32 v113, v154, v154
	v_add_f32_e32 v112, v112, v113
	v_mul_f32_e32 v113, v157, v157
	v_fmac_f32_e32 v113, v156, v156
	v_add_f32_e32 v112, v113, v112
	global_store_dwordx4 v[126:127], v[116:119], off offset:512
	global_store_dwordx4 v[126:127], v[154:157], off offset:528
	v_add_f32_e32 v114, v162, v112
	v_lshl_add_u64 v[112:113], s[42:43], 0, v[148:149]
	v_pk_add_f32 v[146:147], v[222:223], 1.0 op_sel_hi:[1,0]
	v_pk_add_f32 v[158:159], v[226:227], 1.0 op_sel_hi:[1,0]
	v_pk_add_f32 v[126:127], v[228:229], 1.0 op_sel_hi:[1,0]
	v_pk_mul_f32 v[116:117], v[116:117], v[158:159]
	v_pk_mul_f32 v[118:119], v[118:119], v[126:127]
	v_cvt_pk_bf16_f32 v116, v116, v117
	v_pk_mul_f32 v[146:147], v[154:155], v[146:147]
	v_cvt_pk_bf16_f32 v117, v118, v119
	v_pk_add_f32 v[148:149], v[224:225], 1.0 op_sel_hi:[1,0]
	v_pk_mul_f32 v[126:127], v[156:157], v[148:149]
	v_cvt_pk_bf16_f32 v118, v146, v147
	v_cvt_pk_bf16_f32 v119, v126, v127
	v_mov_b32_e32 v115, v114
	global_store_dwordx4 v[124:125], v[116:119], off offset:256
	s_nop 0
	v_permlane16_swap_b32_e32 v114, v115
	s_nop 0
	v_add_f32_e32 v114, v114, v115
	v_mov_b32_e32 v115, v114
	s_nop 1
	v_permlane32_swap_b32_e32 v114, v115
	s_and_saveexec_b64 s[10:11], s[38:39]
	s_cbranch_execz .LBB0_64
	v_lshl_add_u64 v[116:117], v[144:145], 2, s[62:63]
	v_add_f32_e32 v114, v114, v115
	global_atomic_add_f32 v[116:117], v114, off
;     __device__ __forceinline__ void operator()(const f32x4 (&acc)[2][2][4][2], const pg8::Unit& u, int wr, int wc, int fr, int fq) const {
;     ...
;                     } else if constexpr (MODE == 7) {
;                         const f32x4 g0 = *(const f32x4*)(vec + col), g1 = *(const f32x4*)(vec + col + 4);
;                         const f32x4 x0 = *(const f32x4*)(xsrc + row * DM + col), x1 = *(const f32x4*)(xsrc + row * DM + col + 4);
;                         const f32x4 y0 = x0 + g0 * v0, y1 = x1 + g1 * v1;
;                         *(f32x4*)(of + row * DM + col) = y0; *(f32x4*)(of + row * DM + col + 4) = y1;
;                         ssq += (y0[0] * y0[0] + y0[1] * y0[1]) + (y0[2] * y0[2] + y0[3] * y0[3]) + (y1[0] * y1[0] + y1[1] * y1[1]) + (y1[2] * y1[2] + y1[3] * y1[3]);
;                         const f32x4 s0 = *(const f32x4*)(vec2 + col) + 1.f, s1 = *(const f32x4*)(vec2 + col + 4) + 1.f;
;                         const f32x4 a0 = y0 * s0, a1 = y1 * s1;
;                         u32x4 w; w.x = pk2(a0[0], a0[1]); w.y = pk2(a0[2], a0[3]); w.z = pk2(a1[0], a1[1]); w.w = pk2(a1[2], a1[3]);
;                         *(u32x4*)(ob + row * DM + col) = w;
;                     } else if constexpr (MODE == 8) {
;                         const f32x4 b0 = *(const f32x4*)(vec + col), b1 = *(const f32x4*)(vec + col + 4);
;                         float r[8] = {v0[0] * rstd + b0[0], v0[1] * rstd + b0[1], v0[2] * rstd + b0[2], v0[3] * rstd + b0[3], v1[0] * rstd + b1[0], v1[1] * rstd + b1[1], v1[2] * rstd + b1[2], v1[3] * rstd + b1[3]};
; #pragma unroll
;                         for (int i = 0; i < 8; ++i) { const float q = fmaxf(r[i], 0.f); r[i] = q * q; }
;                         u32x4 w; w.x = pk2(r[0], r[1]); w.y = pk2(r[2], r[3]); w.z = pk2(r[4], r[5]); w.w = pk2(r[6], r[7]);
;                         *(u32x4*)(ob + row * HIDN + col) = w;
;                     } else {
;                         float r[8] = {v0[0], v0[1], v0[2], v0[3], v1[0], v1[1], v1[2], v1[3]};
; #pragma unroll
;                         for (int i = 0; i < 8; ++i) { const float q = fmaxf(r[i], 0.f); r[i] = q * q; }
;                         u32x4 w; w.x = pk2(r[0], r[1]); w.y = pk2(r[2], r[3]); w.z = pk2(r[4], r[5]); w.w = pk2(r[6], r[7]);
;                         *(u32x4*)(ob + row * HIDN + col) = w;
;                     }
;                 }
;                 if constexpr (MODE == 7) {
.LBB0_64:
	s_or_b64 exec, exec, s[10:11]
	v_or_b32_e32 v114, 16, v144
	v_ashrrev_i32_e32 v115, 31, v114
	v_lshlrev_b64 v[118:119], 13, v[114:115]
	v_lshl_add_u64 v[116:117], s[30:31], 0, v[118:119]
	v_lshl_add_u64 v[116:117], v[116:117], 0, v[140:141]
	global_load_dwordx4 v[196:199], v[142:143], off offset:16
	global_load_dwordx4 v[200:203], v[142:143], off
	global_load_dwordx4 v[214:217], v[116:117], off offset:16
	global_load_dwordx4 v[218:221], v[116:117], off
	global_load_dwordx4 v[222:225], v[120:121], off offset:16
	global_load_dwordx4 v[226:229], v[120:121], off
	s_waitcnt vmcnt(0)
	v_pk_fma_f32 v[106:107], v[106:107], v[198:199], v[216:217]
	v_pk_fma_f32 v[146:147], v[108:109], v[200:201], v[218:219]
	v_lshl_add_u64 v[108:109], s[6:7], 0, v[118:119]
	v_pk_fma_f32 v[148:149], v[110:111], v[202:203], v[220:221]
	v_lshl_add_u64 v[108:109], v[108:109], 0, v[140:141]
	v_pk_fma_f32 v[104:105], v[104:105], v[196:197], v[214:215]
	global_store_dwordx4 v[108:109], v[146:149], off
	global_store_dwordx4 v[108:109], v[104:107], off offset:16
	v_mul_f32_e32 v110, v147, v147
	v_mul_f32_e32 v111, v149, v149
	v_fmac_f32_e32 v110, v146, v146
	v_fmac_f32_e32 v111, v148, v148
	v_add_f32_e32 v110, v110, v111
	v_mul_f32_e32 v111, v105, v105
	v_fmac_f32_e32 v111, v104, v104
	v_add_f32_e32 v110, v110, v111
	v_mul_f32_e32 v111, v107, v107
	v_fmac_f32_e32 v111, v106, v106
	v_add_f32_e32 v145, v111, v110
	v_pk_add_f32 v[126:127], v[224:225], 1.0 op_sel_hi:[1,0]
	v_pk_add_f32 v[118:119], v[226:227], 1.0 op_sel_hi:[1,0]
	v_pk_add_f32 v[124:125], v[222:223], 1.0 op_sel_hi:[1,0]
	v_pk_mul_f32 v[118:119], v[146:147], v[118:119]
	v_pk_mul_f32 v[126:127], v[106:107], v[126:127]
	v_pk_mul_f32 v[106:107], v[104:105], v[124:125]
	v_pk_add_f32 v[110:111], v[228:229], 1.0 op_sel_hi:[1,0]
	v_pk_mul_f32 v[110:111], v[148:149], v[110:111]
	v_cvt_pk_bf16_f32 v104, v118, v119
	v_cvt_pk_bf16_f32 v105, v110, v111
	v_cvt_pk_bf16_f32 v106, v106, v107
	v_cvt_pk_bf16_f32 v107, v126, v127
	v_lshlrev_b64 v[110:111], 12, v[114:115]
	v_lshl_add_u64 v[110:111], s[28:29], 0, v[110:111]
	v_lshl_add_u64 v[110:111], v[138:139], 1, v[110:111]
	global_store_dwordx4 v[110:111], v[104:107], off
	global_load_dwordx4 v[196:199], v[122:123], off offset:16
	global_load_dwordx4 v[200:203], v[122:123], off
	global_load_dwordx4 v[214:217], v[116:117], off offset:528
	global_load_dwordx4 v[218:221], v[116:117], off offset:512
	global_load_dwordx4 v[222:225], v[112:113], off offset:16
	global_load_dwordx4 v[226:229], v[112:113], off
	s_nop 0
	s_nop 0
	s_waitcnt vmcnt(0)
	v_pk_fma_f32 v[96:97], v[96:97], v[196:197], v[214:215]
	v_pk_fma_f32 v[102:103], v[102:103], v[202:203], v[220:221]
	v_pk_fma_f32 v[100:101], v[100:101], v[200:201], v[218:219]
	v_mul_f32_e32 v105, v103, v103
	v_mul_f32_e32 v104, v101, v101
	v_fmac_f32_e32 v104, v100, v100
	v_fmac_f32_e32 v105, v102, v102
	v_add_f32_e32 v104, v104, v105
	v_mul_f32_e32 v105, v97, v97
	v_pk_fma_f32 v[98:99], v[98:99], v[198:199], v[216:217]
	v_fmac_f32_e32 v105, v96, v96
	v_add_f32_e32 v104, v104, v105
	v_mul_f32_e32 v105, v99, v99
	v_fmac_f32_e32 v105, v98, v98
	global_store_dwordx4 v[108:109], v[100:103], off offset:512
	global_store_dwordx4 v[108:109], v[96:99], off offset:528
	v_add_f32_e32 v104, v105, v104
	v_add_f32_e32 v124, v145, v104
	v_pk_add_f32 v[106:107], v[224:225], 1.0 op_sel_hi:[1,0]
	v_pk_add_f32 v[116:117], v[226:227], 1.0 op_sel_hi:[1,0]
	v_pk_add_f32 v[104:105], v[222:223], 1.0 op_sel_hi:[1,0]
	v_pk_mul_f32 v[100:101], v[100:101], v[116:117]
	v_pk_mul_f32 v[106:107], v[98:99], v[106:107]
	v_pk_mul_f32 v[98:99], v[96:97], v[104:105]
	v_pk_add_f32 v[108:109], v[228:229], 1.0 op_sel_hi:[1,0]
	v_pk_mul_f32 v[102:103], v[102:103], v[108:109]
	v_cvt_pk_bf16_f32 v96, v100, v101
	v_cvt_pk_bf16_f32 v97, v102, v103
	v_cvt_pk_bf16_f32 v98, v98, v99
	v_cvt_pk_bf16_f32 v99, v106, v107
	global_store_dwordx4 v[110:111], v[96:99], off offset:256
	s_nop 1
	v_mov_b32_e32 v96, v124
	s_nop 1
	v_permlane16_swap_b32_e32 v124, v96
	s_nop 0
	v_add_f32_e32 v96, v124, v96
	v_mov_b32_e32 v97, v96
	s_nop 1
	v_permlane32_swap_b32_e32 v96, v97
	s_and_saveexec_b64 s[10:11], s[38:39]
	s_cbranch_execz .LBB0_66
	v_lshl_add_u64 v[98:99], v[114:115], 2, s[62:63]
	v_add_f32_e32 v96, v96, v97
	global_atomic_add_f32 v[98:99], v96, off
;     __device__ __forceinline__ void operator()(const f32x4 (&acc)[2][2][4][2], const pg8::Unit& u, int wr, int wc, int fr, int fq) const {
;     ...
;                     } else if constexpr (MODE == 7) {
;                         const f32x4 g0 = *(const f32x4*)(vec + col), g1 = *(const f32x4*)(vec + col + 4);
;                         const f32x4 x0 = *(const f32x4*)(xsrc + row * DM + col), x1 = *(const f32x4*)(xsrc + row * DM + col + 4);
;                         const f32x4 y0 = x0 + g0 * v0, y1 = x1 + g1 * v1;
;                         *(f32x4*)(of + row * DM + col) = y0; *(f32x4*)(of + row * DM + col + 4) = y1;
;                         ssq += (y0[0] * y0[0] + y0[1] * y0[1]) + (y0[2] * y0[2] + y0[3] * y0[3]) + (y1[0] * y1[0] + y1[1] * y1[1]) + (y1[2] * y1[2] + y1[3] * y1[3]);
;                         const f32x4 s0 = *(const f32x4*)(vec2 + col) + 1.f, s1 = *(const f32x4*)(vec2 + col + 4) + 1.f;
;                         const f32x4 a0 = y0 * s0, a1 = y1 * s1;
;                         u32x4 w; w.x = pk2(a0[0], a0[1]); w.y = pk2(a0[2], a0[3]); w.z = pk2(a1[0], a1[1]); w.w = pk2(a1[2], a1[3]);
;                         *(u32x4*)(ob + row * DM + col) = w;
;                     } else if constexpr (MODE == 8) {
;                         const f32x4 b0 = *(const f32x4*)(vec + col), b1 = *(const f32x4*)(vec + col + 4);
;                         float r[8] = {v0[0] * rstd + b0[0], v0[1] * rstd + b0[1], v0[2] * rstd + b0[2], v0[3] * rstd + b0[3], v1[0] * rstd + b1[0], v1[1] * rstd + b1[1], v1[2] * rstd + b1[2], v1[3] * rstd + b1[3]};
; #pragma unroll
;                         for (int i = 0; i < 8; ++i) { const float q = fmaxf(r[i], 0.f); r[i] = q * q; }
;                         u32x4 w; w.x = pk2(r[0], r[1]); w.y = pk2(r[2], r[3]); w.z = pk2(r[4], r[5]); w.w = pk2(r[6], r[7]);
;                         *(u32x4*)(ob + row * HIDN + col) = w;
;                     } else {
;                         float r[8] = {v0[0], v0[1], v0[2], v0[3], v1[0], v1[1], v1[2], v1[3]};
; #pragma unroll
;                         for (int i = 0; i < 8; ++i) { const float q = fmaxf(r[i], 0.f); r[i] = q * q; }
;                         u32x4 w; w.x = pk2(r[0], r[1]); w.y = pk2(r[2], r[3]); w.z = pk2(r[4], r[5]); w.w = pk2(r[6], r[7]);
;                         *(u32x4*)(ob + row * HIDN + col) = w;
;                     }
;                 }
;                 if constexpr (MODE == 7) {
.LBB0_66:
	s_or_b64 exec, exec, s[10:11]
	v_or_b32_e32 v96, 32, v144
	v_ashrrev_i32_e32 v97, 31, v96
	v_lshlrev_b64 v[118:119], 13, v[96:97]
	v_lshl_add_u64 v[98:99], s[30:31], 0, v[118:119]
	v_lshl_add_u64 v[98:99], v[98:99], 0, v[140:141]
	global_load_dwordx4 v[196:199], v[142:143], off offset:16
	global_load_dwordx4 v[200:203], v[142:143], off
	global_load_dwordx4 v[214:217], v[98:99], off offset:16
	global_load_dwordx4 v[218:221], v[98:99], off
	global_load_dwordx4 v[222:225], v[120:121], off offset:16
	global_load_dwordx4 v[226:229], v[120:121], off
	s_waitcnt vmcnt(0)
	v_pk_fma_f32 v[90:91], v[90:91], v[198:199], v[216:217]
	v_pk_fma_f32 v[104:105], v[92:93], v[200:201], v[218:219]
	v_lshl_add_u64 v[92:93], s[6:7], 0, v[118:119]
	v_pk_fma_f32 v[106:107], v[94:95], v[202:203], v[220:221]
	v_lshl_add_u64 v[92:93], v[92:93], 0, v[140:141]
	v_pk_fma_f32 v[88:89], v[88:89], v[196:197], v[214:215]
	global_store_dwordx4 v[92:93], v[104:107], off
	global_store_dwordx4 v[92:93], v[88:91], off offset:16
	v_mul_f32_e32 v94, v105, v105
	v_mul_f32_e32 v95, v107, v107
	v_fmac_f32_e32 v94, v104, v104
	v_fmac_f32_e32 v95, v106, v106
	v_add_f32_e32 v94, v94, v95
	v_mul_f32_e32 v95, v89, v89
	v_fmac_f32_e32 v95, v88, v88
	v_add_f32_e32 v94, v94, v95
	v_mul_f32_e32 v95, v91, v91
	v_fmac_f32_e32 v95, v90, v90
	v_add_f32_e32 v114, v95, v94
	v_pk_add_f32 v[102:103], v[224:225], 1.0 op_sel_hi:[1,0]
	v_pk_add_f32 v[108:109], v[226:227], 1.0 op_sel_hi:[1,0]
	v_pk_add_f32 v[100:101], v[222:223], 1.0 op_sel_hi:[1,0]
	v_pk_mul_f32 v[104:105], v[104:105], v[108:109]
	v_pk_mul_f32 v[102:103], v[90:91], v[102:103]
	v_pk_mul_f32 v[90:91], v[88:89], v[100:101]
	v_pk_add_f32 v[94:95], v[228:229], 1.0 op_sel_hi:[1,0]
	v_pk_mul_f32 v[94:95], v[106:107], v[94:95]
	v_cvt_pk_bf16_f32 v88, v104, v105
	v_cvt_pk_bf16_f32 v89, v94, v95
	v_cvt_pk_bf16_f32 v90, v90, v91
	v_cvt_pk_bf16_f32 v91, v102, v103
	v_lshlrev_b64 v[94:95], 12, v[96:97]
	v_lshl_add_u64 v[94:95], s[28:29], 0, v[94:95]
	v_lshl_add_u64 v[94:95], v[138:139], 1, v[94:95]
	global_store_dwordx4 v[94:95], v[88:91], off
	global_load_dwordx4 v[196:199], v[122:123], off offset:16
	global_load_dwordx4 v[200:203], v[122:123], off
	global_load_dwordx4 v[214:217], v[98:99], off offset:528
	global_load_dwordx4 v[218:221], v[98:99], off offset:512
	global_load_dwordx4 v[222:225], v[112:113], off offset:16
	global_load_dwordx4 v[226:229], v[112:113], off
	s_nop 0
	s_waitcnt vmcnt(0)
	v_pk_fma_f32 v[80:81], v[80:81], v[196:197], v[214:215]
	v_pk_fma_f32 v[86:87], v[86:87], v[202:203], v[220:221]
	v_pk_fma_f32 v[84:85], v[84:85], v[200:201], v[218:219]
	v_mul_f32_e32 v89, v87, v87
	v_mul_f32_e32 v88, v85, v85
	v_fmac_f32_e32 v88, v84, v84
	v_fmac_f32_e32 v89, v86, v86
	v_add_f32_e32 v88, v88, v89
	v_mul_f32_e32 v89, v81, v81
	v_pk_fma_f32 v[82:83], v[82:83], v[198:199], v[216:217]
	v_fmac_f32_e32 v89, v80, v80
	v_add_f32_e32 v88, v88, v89
	v_mul_f32_e32 v89, v83, v83
	v_fmac_f32_e32 v89, v82, v82
	global_store_dwordx4 v[92:93], v[84:87], off offset:512
	global_store_dwordx4 v[92:93], v[80:83], off offset:528
	v_add_f32_e32 v88, v89, v88
	v_add_f32_e32 v102, v114, v88
	v_pk_add_f32 v[90:91], v[224:225], 1.0 op_sel_hi:[1,0]
	v_pk_add_f32 v[98:99], v[226:227], 1.0 op_sel_hi:[1,0]
	v_pk_add_f32 v[88:89], v[222:223], 1.0 op_sel_hi:[1,0]
	v_pk_mul_f32 v[84:85], v[84:85], v[98:99]
	v_pk_mul_f32 v[90:91], v[82:83], v[90:91]
	v_pk_mul_f32 v[82:83], v[80:81], v[88:89]
	v_pk_add_f32 v[92:93], v[228:229], 1.0 op_sel_hi:[1,0]
	v_pk_mul_f32 v[86:87], v[86:87], v[92:93]
	v_cvt_pk_bf16_f32 v80, v84, v85
	v_cvt_pk_bf16_f32 v81, v86, v87
	v_cvt_pk_bf16_f32 v82, v82, v83
	v_cvt_pk_bf16_f32 v83, v90, v91
	global_store_dwordx4 v[94:95], v[80:83], off offset:256
	s_nop 1
	v_mov_b32_e32 v80, v102
	s_nop 1
	v_permlane16_swap_b32_e32 v102, v80
	s_nop 0
	v_add_f32_e32 v80, v102, v80
	v_mov_b32_e32 v81, v80
	s_nop 1
	v_permlane32_swap_b32_e32 v80, v81
	s_and_saveexec_b64 s[10:11], s[38:39]
	s_cbranch_execz .LBB0_68
	v_lshl_add_u64 v[82:83], v[96:97], 2, s[62:63]
	v_add_f32_e32 v80, v80, v81
	global_atomic_add_f32 v[82:83], v80, off
.LBB0_68:
	s_or_b64 exec, exec, s[10:11]
	v_or_b32_e32 v80, 48, v144
	v_ashrrev_i32_e32 v81, 31, v80
	v_lshlrev_b64 v[100:101], 13, v[80:81]
	v_lshl_add_u64 v[82:83], s[30:31], 0, v[100:101]
	v_lshl_add_u64 v[82:83], v[82:83], 0, v[140:141]
	global_load_dwordx4 v[196:199], v[142:143], off offset:16
	global_load_dwordx4 v[200:203], v[142:143], off
	global_load_dwordx4 v[214:217], v[82:83], off offset:16
	global_load_dwordx4 v[218:221], v[82:83], off
	global_load_dwordx4 v[222:225], v[120:121], off offset:16
	global_load_dwordx4 v[226:229], v[120:121], off
	s_waitcnt vmcnt(0)
	v_pk_fma_f32 v[74:75], v[74:75], v[198:199], v[216:217]
	v_pk_fma_f32 v[88:89], v[76:77], v[200:201], v[218:219]
	v_lshl_add_u64 v[76:77], s[6:7], 0, v[100:101]
	v_pk_fma_f32 v[90:91], v[78:79], v[202:203], v[220:221]
	v_lshl_add_u64 v[76:77], v[76:77], 0, v[140:141]
	v_pk_fma_f32 v[72:73], v[72:73], v[196:197], v[214:215]
	global_store_dwordx4 v[76:77], v[88:91], off
	global_store_dwordx4 v[76:77], v[72:75], off offset:16
	v_mul_f32_e32 v78, v89, v89
	v_mul_f32_e32 v79, v91, v91
	v_fmac_f32_e32 v78, v88, v88
	v_fmac_f32_e32 v79, v90, v90
	v_add_f32_e32 v78, v78, v79
	v_mul_f32_e32 v79, v73, v73
	v_fmac_f32_e32 v79, v72, v72
	v_add_f32_e32 v78, v78, v79
	v_mul_f32_e32 v79, v75, v75
	v_fmac_f32_e32 v79, v74, v74
	v_add_f32_e32 v96, v79, v78
	v_pk_add_f32 v[86:87], v[224:225], 1.0 op_sel_hi:[1,0]
	v_pk_add_f32 v[92:93], v[226:227], 1.0 op_sel_hi:[1,0]
	v_pk_add_f32 v[84:85], v[222:223], 1.0 op_sel_hi:[1,0]
	v_pk_mul_f32 v[88:89], v[88:89], v[92:93]
	v_pk_mul_f32 v[86:87], v[74:75], v[86:87]
	v_pk_mul_f32 v[74:75], v[72:73], v[84:85]
	v_pk_add_f32 v[78:79], v[228:229], 1.0 op_sel_hi:[1,0]
	v_pk_mul_f32 v[78:79], v[90:91], v[78:79]
	v_cvt_pk_bf16_f32 v72, v88, v89
	v_cvt_pk_bf16_f32 v73, v78, v79
	v_cvt_pk_bf16_f32 v74, v74, v75
	v_cvt_pk_bf16_f32 v75, v86, v87
	v_lshlrev_b64 v[78:79], 12, v[80:81]
	v_lshl_add_u64 v[78:79], s[28:29], 0, v[78:79]
	v_lshl_add_u64 v[78:79], v[138:139], 1, v[78:79]
	global_store_dwordx4 v[78:79], v[72:75], off
	global_load_dwordx4 v[196:199], v[122:123], off offset:16
	global_load_dwordx4 v[200:203], v[122:123], off
	global_load_dwordx4 v[214:217], v[82:83], off offset:528
	global_load_dwordx4 v[218:221], v[82:83], off offset:512
	global_load_dwordx4 v[222:225], v[112:113], off offset:16
	global_load_dwordx4 v[226:229], v[112:113], off
	s_nop 0
	s_waitcnt vmcnt(0)
;     __device__ __forceinline__ void operator()(const f32x4 (&acc)[2][2][4][2], const pg8::Unit& u, int wr, int wc, int fr, int fq) const {
;     ...
;                     } else if constexpr (MODE == 7) {
;                         const f32x4 g0 = *(const f32x4*)(vec + col), g1 = *(const f32x4*)(vec + col + 4);
;                         const f32x4 x0 = *(const f32x4*)(xsrc + row * DM + col), x1 = *(const f32x4*)(xsrc + row * DM + col + 4);
;                         const f32x4 y0 = x0 + g0 * v0, y1 = x1 + g1 * v1;
;                         *(f32x4*)(of + row * DM + col) = y0; *(f32x4*)(of + row * DM + col + 4) = y1;
;                         ssq += (y0[0] * y0[0] + y0[1] * y0[1]) + (y0[2] * y0[2] + y0[3] * y0[3]) + (y1[0] * y1[0] + y1[1] * y1[1]) + (y1[2] * y1[2] + y1[3] * y1[3]);
;                         const f32x4 s0 = *(const f32x4*)(vec2 + col) + 1.f, s1 = *(const f32x4*)(vec2 + col + 4) + 1.f;
;                         const f32x4 a0 = y0 * s0, a1 = y1 * s1;
;                         u32x4 w; w.x = pk2(a0[0], a0[1]); w.y = pk2(a0[2], a0[3]); w.z = pk2(a1[0], a1[1]); w.w = pk2(a1[2], a1[3]);
;                         *(u32x4*)(ob + row * DM + col) = w;
;                     } else if constexpr (MODE == 8) {
;                         const f32x4 b0 = *(const f32x4*)(vec + col), b1 = *(const f32x4*)(vec + col + 4);
;                         float r[8] = {v0[0] * rstd + b0[0], v0[1] * rstd + b0[1], v0[2] * rstd + b0[2], v0[3] * rstd + b0[3], v1[0] * rstd + b1[0], v1[1] * rstd + b1[1], v1[2] * rstd + b1[2], v1[3] * rstd + b1[3]};
; #pragma unroll
;                         for (int i = 0; i < 8; ++i) { const float q = fmaxf(r[i], 0.f); r[i] = q * q; }
;                         u32x4 w; w.x = pk2(r[0], r[1]); w.y = pk2(r[2], r[3]); w.z = pk2(r[4], r[5]); w.w = pk2(r[6], r[7]);
;                         *(u32x4*)(ob + row * HIDN + col) = w;
;                     } else {
;                         float r[8] = {v0[0], v0[1], v0[2], v0[3], v1[0], v1[1], v1[2], v1[3]};
; #pragma unroll
;                         for (int i = 0; i < 8; ++i) { const float q = fmaxf(r[i], 0.f); r[i] = q * q; }
;                         u32x4 w; w.x = pk2(r[0], r[1]); w.y = pk2(r[2], r[3]); w.z = pk2(r[4], r[5]); w.w = pk2(r[6], r[7]);
;                         *(u32x4*)(ob + row * HIDN + col) = w;
;                     }
;                 }
;                 if constexpr (MODE == 7) {
	v_pk_fma_f32 v[64:65], v[64:65], v[196:197], v[214:215]
	v_pk_fma_f32 v[70:71], v[70:71], v[202:203], v[220:221]
	v_pk_fma_f32 v[68:69], v[68:69], v[200:201], v[218:219]
	v_mul_f32_e32 v73, v71, v71
	v_mul_f32_e32 v72, v69, v69
	v_fmac_f32_e32 v72, v68, v68
	v_fmac_f32_e32 v73, v70, v70
	v_add_f32_e32 v72, v72, v73
	v_mul_f32_e32 v73, v65, v65
	v_pk_fma_f32 v[66:67], v[66:67], v[198:199], v[216:217]
	v_fmac_f32_e32 v73, v64, v64
	v_add_f32_e32 v72, v72, v73
	v_mul_f32_e32 v73, v67, v67
	v_fmac_f32_e32 v73, v66, v66
	global_store_dwordx4 v[76:77], v[68:71], off offset:512
	global_store_dwordx4 v[76:77], v[64:67], off offset:528
	v_add_f32_e32 v72, v73, v72
	v_add_f32_e32 v86, v96, v72
	v_pk_add_f32 v[74:75], v[224:225], 1.0 op_sel_hi:[1,0]
	v_pk_add_f32 v[82:83], v[226:227], 1.0 op_sel_hi:[1,0]
	v_pk_add_f32 v[72:73], v[222:223], 1.0 op_sel_hi:[1,0]
	v_pk_mul_f32 v[68:69], v[68:69], v[82:83]
	v_pk_mul_f32 v[74:75], v[66:67], v[74:75]
	v_pk_mul_f32 v[66:67], v[64:65], v[72:73]
	v_pk_add_f32 v[76:77], v[228:229], 1.0 op_sel_hi:[1,0]
	v_pk_mul_f32 v[70:71], v[70:71], v[76:77]
	v_cvt_pk_bf16_f32 v64, v68, v69
	v_cvt_pk_bf16_f32 v65, v70, v71
	v_cvt_pk_bf16_f32 v66, v66, v67
	v_cvt_pk_bf16_f32 v67, v74, v75
	global_store_dwordx4 v[78:79], v[64:67], off offset:256
	s_nop 1
	v_mov_b32_e32 v64, v86
	s_nop 1
	v_permlane16_swap_b32_e32 v86, v64
	s_nop 0
	v_add_f32_e32 v64, v86, v64
	v_mov_b32_e32 v65, v64
	s_nop 1
	v_permlane32_swap_b32_e32 v64, v65
	s_and_saveexec_b64 s[10:11], s[38:39]
	s_cbranch_execz .LBB0_70
	v_lshl_add_u64 v[66:67], v[80:81], 2, s[62:63]
	v_add_f32_e32 v64, v64, v65
	global_atomic_add_f32 v[66:67], v64, off
.LBB0_70:
	s_or_b64 exec, exec, s[10:11]
	v_add_u32_e32 v64, 0x80, v144
	v_ashrrev_i32_e32 v65, 31, v64
	v_lshlrev_b64 v[84:85], 13, v[64:65]
	v_lshl_add_u64 v[66:67], s[30:31], 0, v[84:85]
	v_lshl_add_u64 v[66:67], v[66:67], 0, v[140:141]
	global_load_dwordx4 v[196:199], v[142:143], off offset:16
	global_load_dwordx4 v[200:203], v[142:143], off
	global_load_dwordx4 v[214:217], v[66:67], off offset:16
	global_load_dwordx4 v[218:221], v[66:67], off
	global_load_dwordx4 v[222:225], v[120:121], off offset:16
	global_load_dwordx4 v[226:229], v[120:121], off
	s_waitcnt vmcnt(0)
	v_pk_fma_f32 v[58:59], v[58:59], v[198:199], v[216:217]
	v_pk_fma_f32 v[72:73], v[60:61], v[200:201], v[218:219]
	v_lshl_add_u64 v[60:61], s[6:7], 0, v[84:85]
	v_pk_fma_f32 v[74:75], v[62:63], v[202:203], v[220:221]
	v_lshl_add_u64 v[60:61], v[60:61], 0, v[140:141]
	v_pk_fma_f32 v[56:57], v[56:57], v[196:197], v[214:215]
	global_store_dwordx4 v[60:61], v[72:75], off
	global_store_dwordx4 v[60:61], v[56:59], off offset:16
	v_mul_f32_e32 v62, v73, v73
	v_mul_f32_e32 v63, v75, v75
	v_fmac_f32_e32 v62, v72, v72
	v_fmac_f32_e32 v63, v74, v74
	v_add_f32_e32 v62, v62, v63
	v_mul_f32_e32 v63, v57, v57
	v_fmac_f32_e32 v63, v56, v56
	v_add_f32_e32 v62, v62, v63
	v_mul_f32_e32 v63, v59, v59
	v_fmac_f32_e32 v63, v58, v58
	v_add_f32_e32 v80, v63, v62
	v_pk_add_f32 v[70:71], v[224:225], 1.0 op_sel_hi:[1,0]
	v_pk_add_f32 v[76:77], v[226:227], 1.0 op_sel_hi:[1,0]
	v_pk_add_f32 v[68:69], v[222:223], 1.0 op_sel_hi:[1,0]
	v_pk_mul_f32 v[72:73], v[72:73], v[76:77]
	v_pk_mul_f32 v[70:71], v[58:59], v[70:71]
	v_pk_mul_f32 v[58:59], v[56:57], v[68:69]
	v_pk_add_f32 v[62:63], v[228:229], 1.0 op_sel_hi:[1,0]
	v_pk_mul_f32 v[62:63], v[74:75], v[62:63]
	v_cvt_pk_bf16_f32 v56, v72, v73
	v_cvt_pk_bf16_f32 v57, v62, v63
	v_cvt_pk_bf16_f32 v58, v58, v59
	v_cvt_pk_bf16_f32 v59, v70, v71
	v_lshlrev_b64 v[62:63], 12, v[64:65]
	v_lshl_add_u64 v[62:63], s[28:29], 0, v[62:63]
	v_lshl_add_u64 v[62:63], v[138:139], 1, v[62:63]
	global_store_dwordx4 v[62:63], v[56:59], off
	global_load_dwordx4 v[196:199], v[122:123], off offset:16
	global_load_dwordx4 v[200:203], v[122:123], off
	global_load_dwordx4 v[214:217], v[66:67], off offset:528
	global_load_dwordx4 v[218:221], v[66:67], off offset:512
	global_load_dwordx4 v[222:225], v[112:113], off offset:16
	global_load_dwordx4 v[226:229], v[112:113], off
	s_nop 0
	s_waitcnt vmcnt(0)
	v_pk_fma_f32 v[48:49], v[48:49], v[196:197], v[214:215]
	v_pk_fma_f32 v[54:55], v[54:55], v[202:203], v[220:221]
	v_pk_fma_f32 v[52:53], v[52:53], v[200:201], v[218:219]
	v_mul_f32_e32 v57, v55, v55
	v_mul_f32_e32 v56, v53, v53
	v_fmac_f32_e32 v56, v52, v52
	v_fmac_f32_e32 v57, v54, v54
	v_add_f32_e32 v56, v56, v57
	v_mul_f32_e32 v57, v49, v49
	v_pk_fma_f32 v[50:51], v[50:51], v[198:199], v[216:217]
	v_fmac_f32_e32 v57, v48, v48
	v_add_f32_e32 v56, v56, v57
	v_mul_f32_e32 v57, v51, v51
	v_fmac_f32_e32 v57, v50, v50
	global_store_dwordx4 v[60:61], v[52:55], off offset:512
	global_store_dwordx4 v[60:61], v[48:51], off offset:528
	v_add_f32_e32 v56, v57, v56
	v_add_f32_e32 v70, v80, v56
	v_pk_add_f32 v[58:59], v[224:225], 1.0 op_sel_hi:[1,0]
	v_pk_add_f32 v[66:67], v[226:227], 1.0 op_sel_hi:[1,0]
	v_pk_add_f32 v[56:57], v[222:223], 1.0 op_sel_hi:[1,0]
	v_pk_mul_f32 v[52:53], v[52:53], v[66:67]
	v_pk_mul_f32 v[58:59], v[50:51], v[58:59]
	v_pk_mul_f32 v[50:51], v[48:49], v[56:57]
	v_pk_add_f32 v[60:61], v[228:229], 1.0 op_sel_hi:[1,0]
	v_pk_mul_f32 v[54:55], v[54:55], v[60:61]
	v_cvt_pk_bf16_f32 v48, v52, v53
	v_cvt_pk_bf16_f32 v49, v54, v55
	v_cvt_pk_bf16_f32 v50, v50, v51
	v_cvt_pk_bf16_f32 v51, v58, v59
	global_store_dwordx4 v[62:63], v[48:51], off offset:256
	s_nop 1
	v_mov_b32_e32 v48, v70
	s_nop 1
	v_permlane16_swap_b32_e32 v70, v48
	s_nop 0
	v_add_f32_e32 v48, v70, v48
	v_mov_b32_e32 v49, v48
	s_nop 1
	v_permlane32_swap_b32_e32 v48, v49
	s_and_saveexec_b64 s[10:11], s[38:39]
	s_cbranch_execz .LBB0_72
	v_lshl_add_u64 v[50:51], v[64:65], 2, s[62:63]
	v_add_f32_e32 v48, v48, v49
	global_atomic_add_f32 v[50:51], v48, off
;     __device__ __forceinline__ void operator()(const f32x4 (&acc)[2][2][4][2], const pg8::Unit& u, int wr, int wc, int fr, int fq) const {
;     ...
;                     } else if constexpr (MODE == 7) {
;                         const f32x4 g0 = *(const f32x4*)(vec + col), g1 = *(const f32x4*)(vec + col + 4);
;                         const f32x4 x0 = *(const f32x4*)(xsrc + row * DM + col), x1 = *(const f32x4*)(xsrc + row * DM + col + 4);
;                         const f32x4 y0 = x0 + g0 * v0, y1 = x1 + g1 * v1;
;                         *(f32x4*)(of + row * DM + col) = y0; *(f32x4*)(of + row * DM + col + 4) = y1;
;                         ssq += (y0[0] * y0[0] + y0[1] * y0[1]) + (y0[2] * y0[2] + y0[3] * y0[3]) + (y1[0] * y1[0] + y1[1] * y1[1]) + (y1[2] * y1[2] + y1[3] * y1[3]);
;                         const f32x4 s0 = *(const f32x4*)(vec2 + col) + 1.f, s1 = *(const f32x4*)(vec2 + col + 4) + 1.f;
;                         const f32x4 a0 = y0 * s0, a1 = y1 * s1;
;                         u32x4 w; w.x = pk2(a0[0], a0[1]); w.y = pk2(a0[2], a0[3]); w.z = pk2(a1[0], a1[1]); w.w = pk2(a1[2], a1[3]);
;                         *(u32x4*)(ob + row * DM + col) = w;
;                     } else if constexpr (MODE == 8) {
;                         const f32x4 b0 = *(const f32x4*)(vec + col), b1 = *(const f32x4*)(vec + col + 4);
;                         float r[8] = {v0[0] * rstd + b0[0], v0[1] * rstd + b0[1], v0[2] * rstd + b0[2], v0[3] * rstd + b0[3], v1[0] * rstd + b1[0], v1[1] * rstd + b1[1], v1[2] * rstd + b1[2], v1[3] * rstd + b1[3]};
; #pragma unroll
;                         for (int i = 0; i < 8; ++i) { const float q = fmaxf(r[i], 0.f); r[i] = q * q; }
;                         u32x4 w; w.x = pk2(r[0], r[1]); w.y = pk2(r[2], r[3]); w.z = pk2(r[4], r[5]); w.w = pk2(r[6], r[7]);
;                         *(u32x4*)(ob + row * HIDN + col) = w;
;                     } else {
;                         float r[8] = {v0[0], v0[1], v0[2], v0[3], v1[0], v1[1], v1[2], v1[3]};
; #pragma unroll
;                         for (int i = 0; i < 8; ++i) { const float q = fmaxf(r[i], 0.f); r[i] = q * q; }
;                         u32x4 w; w.x = pk2(r[0], r[1]); w.y = pk2(r[2], r[3]); w.z = pk2(r[4], r[5]); w.w = pk2(r[6], r[7]);
;                         *(u32x4*)(ob + row * HIDN + col) = w;
;                     }
;                 }
;                 if constexpr (MODE == 7) {
.LBB0_72:
	s_or_b64 exec, exec, s[10:11]
	v_add_u32_e32 v48, 0x90, v144
	v_ashrrev_i32_e32 v49, 31, v48
	v_lshlrev_b64 v[68:69], 13, v[48:49]
	v_lshl_add_u64 v[50:51], s[30:31], 0, v[68:69]
	v_lshl_add_u64 v[50:51], v[50:51], 0, v[140:141]
	global_load_dwordx4 v[196:199], v[142:143], off offset:16
	global_load_dwordx4 v[200:203], v[142:143], off
	global_load_dwordx4 v[214:217], v[50:51], off offset:16
	global_load_dwordx4 v[218:221], v[50:51], off
	global_load_dwordx4 v[222:225], v[120:121], off offset:16
	global_load_dwordx4 v[226:229], v[120:121], off
	s_waitcnt vmcnt(0)
	v_pk_fma_f32 v[42:43], v[42:43], v[198:199], v[216:217]
	v_pk_fma_f32 v[56:57], v[44:45], v[200:201], v[218:219]
	v_lshl_add_u64 v[44:45], s[6:7], 0, v[68:69]
	v_pk_fma_f32 v[58:59], v[46:47], v[202:203], v[220:221]
	v_lshl_add_u64 v[44:45], v[44:45], 0, v[140:141]
	v_pk_fma_f32 v[40:41], v[40:41], v[196:197], v[214:215]
	global_store_dwordx4 v[44:45], v[56:59], off
	global_store_dwordx4 v[44:45], v[40:43], off offset:16
	v_mul_f32_e32 v46, v57, v57
	v_mul_f32_e32 v47, v59, v59
	v_fmac_f32_e32 v46, v56, v56
	v_fmac_f32_e32 v47, v58, v58
	v_add_f32_e32 v46, v46, v47
	v_mul_f32_e32 v47, v41, v41
	v_fmac_f32_e32 v47, v40, v40
	v_add_f32_e32 v46, v46, v47
	v_mul_f32_e32 v47, v43, v43
	v_fmac_f32_e32 v47, v42, v42
	v_add_f32_e32 v64, v47, v46
	v_pk_add_f32 v[54:55], v[224:225], 1.0 op_sel_hi:[1,0]
	v_pk_add_f32 v[60:61], v[226:227], 1.0 op_sel_hi:[1,0]
	v_pk_add_f32 v[52:53], v[222:223], 1.0 op_sel_hi:[1,0]
	v_pk_mul_f32 v[56:57], v[56:57], v[60:61]
	v_pk_mul_f32 v[54:55], v[42:43], v[54:55]
	v_pk_mul_f32 v[42:43], v[40:41], v[52:53]
	v_pk_add_f32 v[46:47], v[228:229], 1.0 op_sel_hi:[1,0]
	v_pk_mul_f32 v[46:47], v[58:59], v[46:47]
	v_cvt_pk_bf16_f32 v40, v56, v57
	v_cvt_pk_bf16_f32 v41, v46, v47
	v_cvt_pk_bf16_f32 v42, v42, v43
	v_cvt_pk_bf16_f32 v43, v54, v55
	v_lshlrev_b64 v[46:47], 12, v[48:49]
	v_lshl_add_u64 v[46:47], s[28:29], 0, v[46:47]
	v_lshl_add_u64 v[46:47], v[138:139], 1, v[46:47]
	global_store_dwordx4 v[46:47], v[40:43], off
	global_load_dwordx4 v[196:199], v[122:123], off offset:16
	global_load_dwordx4 v[200:203], v[122:123], off
	global_load_dwordx4 v[214:217], v[50:51], off offset:528
	global_load_dwordx4 v[218:221], v[50:51], off offset:512
	global_load_dwordx4 v[222:225], v[112:113], off offset:16
	global_load_dwordx4 v[226:229], v[112:113], off
	s_nop 0
	s_waitcnt vmcnt(0)
	v_pk_fma_f32 v[32:33], v[32:33], v[196:197], v[214:215]
	v_pk_fma_f32 v[38:39], v[38:39], v[202:203], v[220:221]
	v_pk_fma_f32 v[36:37], v[36:37], v[200:201], v[218:219]
	v_mul_f32_e32 v41, v39, v39
	v_mul_f32_e32 v40, v37, v37
	v_fmac_f32_e32 v40, v36, v36
	v_fmac_f32_e32 v41, v38, v38
	v_add_f32_e32 v40, v40, v41
	v_mul_f32_e32 v41, v33, v33
	v_pk_fma_f32 v[34:35], v[34:35], v[198:199], v[216:217]
	v_fmac_f32_e32 v41, v32, v32
	v_add_f32_e32 v40, v40, v41
	v_mul_f32_e32 v41, v35, v35
	v_fmac_f32_e32 v41, v34, v34
	global_store_dwordx4 v[44:45], v[36:39], off offset:512
	global_store_dwordx4 v[44:45], v[32:35], off offset:528
	v_add_f32_e32 v40, v41, v40
	v_add_f32_e32 v54, v64, v40
	v_pk_add_f32 v[42:43], v[224:225], 1.0 op_sel_hi:[1,0]
	v_pk_add_f32 v[50:51], v[226:227], 1.0 op_sel_hi:[1,0]
	v_pk_add_f32 v[40:41], v[222:223], 1.0 op_sel_hi:[1,0]
	v_pk_mul_f32 v[36:37], v[36:37], v[50:51]
	v_pk_mul_f32 v[42:43], v[34:35], v[42:43]
	v_pk_mul_f32 v[34:35], v[32:33], v[40:41]
	v_pk_add_f32 v[44:45], v[228:229], 1.0 op_sel_hi:[1,0]
	v_pk_mul_f32 v[38:39], v[38:39], v[44:45]
	v_cvt_pk_bf16_f32 v32, v36, v37
	v_cvt_pk_bf16_f32 v33, v38, v39
	v_cvt_pk_bf16_f32 v34, v34, v35
	v_cvt_pk_bf16_f32 v35, v42, v43
	global_store_dwordx4 v[46:47], v[32:35], off offset:256
	s_nop 1
	v_mov_b32_e32 v32, v54
	s_nop 1
	v_permlane16_swap_b32_e32 v54, v32
	s_nop 0
	v_add_f32_e32 v32, v54, v32
	v_mov_b32_e32 v33, v32
	s_nop 1
	v_permlane32_swap_b32_e32 v32, v33
	s_and_saveexec_b64 s[10:11], s[38:39]
	s_cbranch_execz .LBB0_74
	v_lshl_add_u64 v[34:35], v[48:49], 2, s[62:63]
	v_add_f32_e32 v32, v32, v33
	global_atomic_add_f32 v[34:35], v32, off
.LBB0_74:
	s_or_b64 exec, exec, s[10:11]
	v_add_u32_e32 v32, 0xa0, v144
	v_ashrrev_i32_e32 v33, 31, v32
	v_lshlrev_b64 v[52:53], 13, v[32:33]
	v_lshl_add_u64 v[34:35], s[30:31], 0, v[52:53]
	v_lshl_add_u64 v[34:35], v[34:35], 0, v[140:141]
	global_load_dwordx4 v[196:199], v[142:143], off offset:16
	global_load_dwordx4 v[200:203], v[142:143], off
	global_load_dwordx4 v[214:217], v[34:35], off offset:16
	global_load_dwordx4 v[218:221], v[34:35], off
	global_load_dwordx4 v[222:225], v[120:121], off offset:16
	global_load_dwordx4 v[226:229], v[120:121], off
	s_waitcnt vmcnt(0)
	v_pk_fma_f32 v[26:27], v[26:27], v[198:199], v[216:217]
	v_pk_fma_f32 v[40:41], v[28:29], v[200:201], v[218:219]
	v_lshl_add_u64 v[28:29], s[6:7], 0, v[52:53]
	v_pk_fma_f32 v[42:43], v[30:31], v[202:203], v[220:221]
	v_lshl_add_u64 v[28:29], v[28:29], 0, v[140:141]
	v_pk_fma_f32 v[24:25], v[24:25], v[196:197], v[214:215]
	global_store_dwordx4 v[28:29], v[40:43], off
	global_store_dwordx4 v[28:29], v[24:27], off offset:16
	v_mul_f32_e32 v30, v41, v41
	v_mul_f32_e32 v31, v43, v43
	v_fmac_f32_e32 v30, v40, v40
	v_fmac_f32_e32 v31, v42, v42
	v_add_f32_e32 v30, v30, v31
	v_mul_f32_e32 v31, v25, v25
	v_fmac_f32_e32 v31, v24, v24
	v_add_f32_e32 v30, v30, v31
	v_mul_f32_e32 v31, v27, v27
	v_fmac_f32_e32 v31, v26, v26
	v_add_f32_e32 v48, v31, v30
	v_pk_add_f32 v[38:39], v[224:225], 1.0 op_sel_hi:[1,0]
	v_pk_add_f32 v[44:45], v[226:227], 1.0 op_sel_hi:[1,0]
	v_pk_add_f32 v[36:37], v[222:223], 1.0 op_sel_hi:[1,0]
	v_pk_mul_f32 v[40:41], v[40:41], v[44:45]
	v_pk_mul_f32 v[38:39], v[26:27], v[38:39]
	v_pk_mul_f32 v[26:27], v[24:25], v[36:37]
	v_pk_add_f32 v[30:31], v[228:229], 1.0 op_sel_hi:[1,0]
	v_pk_mul_f32 v[30:31], v[42:43], v[30:31]
	v_cvt_pk_bf16_f32 v24, v40, v41
	v_cvt_pk_bf16_f32 v25, v30, v31
	v_cvt_pk_bf16_f32 v26, v26, v27
	v_cvt_pk_bf16_f32 v27, v38, v39
	v_lshlrev_b64 v[30:31], 12, v[32:33]
	v_lshl_add_u64 v[30:31], s[28:29], 0, v[30:31]
	v_lshl_add_u64 v[30:31], v[138:139], 1, v[30:31]
	global_store_dwordx4 v[30:31], v[24:27], off
	global_load_dwordx4 v[196:199], v[122:123], off offset:16
	global_load_dwordx4 v[200:203], v[122:123], off
	global_load_dwordx4 v[214:217], v[34:35], off offset:528
	global_load_dwordx4 v[218:221], v[34:35], off offset:512
	global_load_dwordx4 v[222:225], v[112:113], off offset:16
	global_load_dwordx4 v[226:229], v[112:113], off
	s_nop 0
	s_waitcnt vmcnt(0)
;     __device__ __forceinline__ void operator()(const f32x4 (&acc)[2][2][4][2], const pg8::Unit& u, int wr, int wc, int fr, int fq) const {
;     ...
;                     } else if constexpr (MODE == 7) {
;                         const f32x4 g0 = *(const f32x4*)(vec + col), g1 = *(const f32x4*)(vec + col + 4);
;                         const f32x4 x0 = *(const f32x4*)(xsrc + row * DM + col), x1 = *(const f32x4*)(xsrc + row * DM + col + 4);
;                         const f32x4 y0 = x0 + g0 * v0, y1 = x1 + g1 * v1;
;                         *(f32x4*)(of + row * DM + col) = y0; *(f32x4*)(of + row * DM + col + 4) = y1;
;                         ssq += (y0[0] * y0[0] + y0[1] * y0[1]) + (y0[2] * y0[2] + y0[3] * y0[3]) + (y1[0] * y1[0] + y1[1] * y1[1]) + (y1[2] * y1[2] + y1[3] * y1[3]);
;                         const f32x4 s0 = *(const f32x4*)(vec2 + col) + 1.f, s1 = *(const f32x4*)(vec2 + col + 4) + 1.f;
;                         const f32x4 a0 = y0 * s0, a1 = y1 * s1;
;                         u32x4 w; w.x = pk2(a0[0], a0[1]); w.y = pk2(a0[2], a0[3]); w.z = pk2(a1[0], a1[1]); w.w = pk2(a1[2], a1[3]);
;                         *(u32x4*)(ob + row * DM + col) = w;
;                     } else if constexpr (MODE == 8) {
;                         const f32x4 b0 = *(const f32x4*)(vec + col), b1 = *(const f32x4*)(vec + col + 4);
;                         float r[8] = {v0[0] * rstd + b0[0], v0[1] * rstd + b0[1], v0[2] * rstd + b0[2], v0[3] * rstd + b0[3], v1[0] * rstd + b1[0], v1[1] * rstd + b1[1], v1[2] * rstd + b1[2], v1[3] * rstd + b1[3]};
; #pragma unroll
;                         for (int i = 0; i < 8; ++i) { const float q = fmaxf(r[i], 0.f); r[i] = q * q; }
;                         u32x4 w; w.x = pk2(r[0], r[1]); w.y = pk2(r[2], r[3]); w.z = pk2(r[4], r[5]); w.w = pk2(r[6], r[7]);
;                         *(u32x4*)(ob + row * HIDN + col) = w;
;                     } else {
;                         float r[8] = {v0[0], v0[1], v0[2], v0[3], v1[0], v1[1], v1[2], v1[3]};
; #pragma unroll
;                         for (int i = 0; i < 8; ++i) { const float q = fmaxf(r[i], 0.f); r[i] = q * q; }
;                         u32x4 w; w.x = pk2(r[0], r[1]); w.y = pk2(r[2], r[3]); w.z = pk2(r[4], r[5]); w.w = pk2(r[6], r[7]);
;                         *(u32x4*)(ob + row * HIDN + col) = w;
;                     }
;                 }
;                 if constexpr (MODE == 7) {
	v_pk_fma_f32 v[16:17], v[16:17], v[196:197], v[214:215]
	v_pk_fma_f32 v[22:23], v[22:23], v[202:203], v[220:221]
	v_pk_fma_f32 v[20:21], v[20:21], v[200:201], v[218:219]
	v_mul_f32_e32 v25, v23, v23
	v_mul_f32_e32 v24, v21, v21
	v_fmac_f32_e32 v24, v20, v20
	v_fmac_f32_e32 v25, v22, v22
	v_add_f32_e32 v24, v24, v25
	v_mul_f32_e32 v25, v17, v17
	v_pk_fma_f32 v[18:19], v[18:19], v[198:199], v[216:217]
	v_fmac_f32_e32 v25, v16, v16
	v_add_f32_e32 v24, v24, v25
	v_mul_f32_e32 v25, v19, v19
	v_fmac_f32_e32 v25, v18, v18
	global_store_dwordx4 v[28:29], v[20:23], off offset:512
	global_store_dwordx4 v[28:29], v[16:19], off offset:528
	v_add_f32_e32 v24, v25, v24
	v_add_f32_e32 v38, v48, v24
	v_pk_add_f32 v[26:27], v[224:225], 1.0 op_sel_hi:[1,0]
	v_pk_add_f32 v[34:35], v[226:227], 1.0 op_sel_hi:[1,0]
	v_pk_add_f32 v[24:25], v[222:223], 1.0 op_sel_hi:[1,0]
	v_pk_mul_f32 v[20:21], v[20:21], v[34:35]
	v_pk_mul_f32 v[26:27], v[18:19], v[26:27]
	v_pk_mul_f32 v[18:19], v[16:17], v[24:25]
	v_pk_add_f32 v[28:29], v[228:229], 1.0 op_sel_hi:[1,0]
	v_pk_mul_f32 v[22:23], v[22:23], v[28:29]
	v_cvt_pk_bf16_f32 v16, v20, v21
	v_cvt_pk_bf16_f32 v17, v22, v23
	v_cvt_pk_bf16_f32 v18, v18, v19
	v_cvt_pk_bf16_f32 v19, v26, v27
	global_store_dwordx4 v[30:31], v[16:19], off offset:256
	s_nop 1
	v_mov_b32_e32 v16, v38
	s_nop 1
	v_permlane16_swap_b32_e32 v38, v16
	s_nop 0
	v_add_f32_e32 v16, v38, v16
	v_mov_b32_e32 v17, v16
	s_nop 1
	v_permlane32_swap_b32_e32 v16, v17
	s_and_saveexec_b64 s[10:11], s[38:39]
	s_cbranch_execz .LBB0_76
	v_lshl_add_u64 v[18:19], v[32:33], 2, s[62:63]
	v_add_f32_e32 v16, v16, v17
	global_atomic_add_f32 v[18:19], v16, off
.LBB0_76:
	s_or_b64 exec, exec, s[10:11]
	v_add_u32_e32 v16, 0xb0, v144
	v_ashrrev_i32_e32 v17, 31, v16
	v_lshlrev_b64 v[34:35], 13, v[16:17]
	v_lshl_add_u64 v[18:19], s[30:31], 0, v[34:35]
	v_lshl_add_u64 v[36:37], v[18:19], 0, v[140:141]
	global_load_dwordx4 v[196:199], v[36:37], off
	global_load_dwordx4 v[200:203], v[142:143], off
	global_load_dwordx4 v[214:217], v[142:143], off offset:16
	global_load_dwordx4 v[218:221], v[36:37], off offset:16
	global_load_dwordx4 v[222:225], v[120:121], off
	global_load_dwordx4 v[226:229], v[120:121], off offset:16
	v_lshl_add_u64 v[34:35], s[6:7], 0, v[34:35]
	v_lshl_add_u64 v[34:35], v[34:35], 0, v[140:141]
	s_waitcnt vmcnt(0)
	v_pk_fma_f32 v[14:15], v[14:15], v[202:203], v[198:199]
	v_pk_fma_f32 v[12:13], v[12:13], v[200:201], v[196:197]
	v_pk_fma_f32 v[10:11], v[10:11], v[216:217], v[220:221]
	v_pk_fma_f32 v[8:9], v[8:9], v[214:215], v[218:219]
	global_store_dwordx4 v[34:35], v[12:15], off
	global_store_dwordx4 v[34:35], v[8:11], off offset:16
	v_lshlrev_b64 v[26:27], 12, v[16:17]
	v_lshl_add_u64 v[26:27], s[28:29], 0, v[26:27]
	v_lshl_add_u64 v[38:39], v[138:139], 1, v[26:27]
	v_pk_add_f32 v[20:21], v[224:225], 1.0 op_sel_hi:[1,0]
	v_pk_add_f32 v[18:19], v[222:223], 1.0 op_sel_hi:[1,0]
	v_pk_add_f32 v[24:25], v[228:229], 1.0 op_sel_hi:[1,0]
	v_pk_add_f32 v[22:23], v[226:227], 1.0 op_sel_hi:[1,0]
	v_pk_mul_f32 v[20:21], v[14:15], v[20:21]
	v_pk_mul_f32 v[18:19], v[12:13], v[18:19]
	v_pk_mul_f32 v[24:25], v[10:11], v[24:25]
	v_pk_mul_f32 v[22:23], v[8:9], v[22:23]
	v_cvt_pk_bf16_f32 v18, v18, v19
	v_cvt_pk_bf16_f32 v19, v20, v21
	v_cvt_pk_bf16_f32 v20, v22, v23
	v_cvt_pk_bf16_f32 v21, v24, v25
	global_store_dwordx4 v[38:39], v[18:21], off
	global_load_dwordx4 v[196:199], v[36:37], off offset:512
	global_load_dwordx4 v[200:203], v[122:123], off
	global_load_dwordx4 v[214:217], v[122:123], off offset:16
	global_load_dwordx4 v[218:221], v[36:37], off offset:528
	global_load_dwordx4 v[222:225], v[112:113], off
	global_load_dwordx4 v[226:229], v[112:113], off offset:16
	s_nop 0
	v_mul_f32_e32 v13, v13, v13
	v_mul_f32_e32 v15, v15, v15
	v_mul_f32_e32 v9, v9, v9
	v_fmac_f32_e32 v13, v12, v12
	v_fmac_f32_e32 v15, v14, v14
	v_mul_f32_e32 v11, v11, v11
	v_fmac_f32_e32 v9, v8, v8
	v_add_f32_e32 v8, v13, v15
	v_fmac_f32_e32 v11, v10, v10
	v_add_f32_e32 v8, v8, v9
	v_add_f32_e32 v8, v11, v8
	s_waitcnt vmcnt(0)
	v_pk_fma_f32 v[6:7], v[6:7], v[202:203], v[198:199]
	v_pk_fma_f32 v[4:5], v[4:5], v[200:201], v[196:197]
	v_pk_fma_f32 v[2:3], v[2:3], v[216:217], v[220:221]
	v_pk_fma_f32 v[0:1], v[0:1], v[214:215], v[218:219]
	global_store_dwordx4 v[34:35], v[4:7], off offset:512
	global_store_dwordx4 v[34:35], v[0:3], off offset:528
	v_mul_f32_e32 v9, v5, v5
	v_mul_f32_e32 v10, v7, v7
	v_mul_f32_e32 v11, v1, v1
	v_fmac_f32_e32 v9, v4, v4
	v_fmac_f32_e32 v10, v6, v6
	v_mul_f32_e32 v12, v3, v3
	v_fmac_f32_e32 v11, v0, v0
	v_add_f32_e32 v9, v9, v10
	v_fmac_f32_e32 v12, v2, v2
	v_add_f32_e32 v9, v9, v11
	v_add_f32_e32 v9, v12, v9
	v_add_f32_e32 v26, v8, v9
	v_mov_b32_e32 v27, v26
	v_pk_add_f32 v[8:9], v[224:225], 1.0 op_sel_hi:[1,0]
	v_pk_add_f32 v[10:11], v[222:223], 1.0 op_sel_hi:[1,0]
	v_pk_add_f32 v[12:13], v[228:229], 1.0 op_sel_hi:[1,0]
	v_pk_add_f32 v[14:15], v[226:227], 1.0 op_sel_hi:[1,0]
	v_pk_mul_f32 v[6:7], v[6:7], v[8:9]
	v_pk_mul_f32 v[4:5], v[4:5], v[10:11]
	v_pk_mul_f32 v[2:3], v[2:3], v[12:13]
	v_pk_mul_f32 v[0:1], v[0:1], v[14:15]
	v_bfe_u32 v12, v0, 16, 1
	v_bfe_u32 v13, v1, 16, 1
	v_add3_u32 v0, v0, v12, s33
	v_add3_u32 v8, v1, v13, s33
	v_cvt_pk_bf16_f32 v1, v6, v7
	v_cvt_pk_bf16_f32 v3, v2, v3
	v_lshrrev_b32_e32 v6, 16, v0
	v_cvt_pk_bf16_f32 v0, v4, v5
	v_and_or_b32 v2, v8, s67, v6
	global_store_dwordx4 v[38:39], v[0:3], off offset:256
	s_nop 0
	v_permlane16_swap_b32_e32 v26, v27
	s_nop 0
	v_add_f32_e32 v0, v26, v27
	v_mov_b32_e32 v1, v0
	s_nop 1
	v_permlane32_swap_b32_e32 v0, v1
	s_and_saveexec_b64 s[10:11], s[38:39]
	s_cbranch_execz .LBB0_78
	v_lshl_add_u64 v[2:3], v[16:17], 2, s[62:63]
	v_add_f32_e32 v0, v0, v1
	global_atomic_add_f32 v[2:3], v0, off

;     __device__ __forceinline__ void operator()(const f32x4 (&acc)[2][2][4][2], const pg8::Unit& u, int wr, int wc, int fr, int fq) const {
;     ...
;         for (int ai = 0; ai < 2; ++ai)
; #pragma unroll
;             for (int m = 0; m < 4; ++m) {
;                 const size_t row = (size_t)(row0 + ai * 128 + m * 16);
;                 float ssq = 0.f, rstd = 1.f;
;                 if constexpr (MODE == 8) rstd = 1.f / sqrtf(rs[row] * (1.f / DM) + EPS);
; #pragma unroll
;                 for (int bj = 0; bj < 2; ++bj) {
;                     const int col = col0 + bj * 128;
;                     f32x4 v0 = acc[ai][bj][m][0], v1 = acc[ai][bj][m][1];
;     ...
;                     } else if constexpr (MODE == 4) {
;                         const f32x4 g0 = *(const f32x4*)(vec + col), g1 = *(const f32x4*)(vec + col + 4);
;                         const f32x4 x0 = *(const f32x4*)(xsrc + row * DM + col), x1 = *(const f32x4*)(xsrc + row * DM + col + 4);
;                         *(f32x4*)(of + row * DM + col) = x0 + g0 * v0; *(f32x4*)(of + row * DM + col + 4) = x1 + g1 * v1;
.LBB0_1151:
	v_lshl_add_u32 v144, s44, 8, v146
	v_lshl_or_b32 v158, s45, 8, v148
	v_ashrrev_i32_e32 v145, 31, v144
	v_ashrrev_i32_e32 v159, 31, v158
	v_lshlrev_b64 v[138:139], 13, v[144:145]
	v_lshlrev_b64 v[142:143], 2, v[158:159]
	v_lshl_add_u64 v[138:139], s[6:7], 0, v[138:139]
	v_lshl_add_u64 v[140:141], s[4:5], 0, v[142:143]
	v_lshl_add_u64 v[138:139], v[138:139], 0, v[142:143]
	global_load_dwordx4 v[192:195], v[140:141], off offset:16
	global_load_dwordx4 v[196:199], v[140:141], off
	global_load_dwordx4 v[200:203], v[138:139], off offset:16
	global_load_dwordx4 v[214:217], v[138:139], off
	v_or_b32_e32 v234, 0x80, v158
	v_ashrrev_i32_e32 v235, 31, v234
	v_lshl_add_u64 v[234:235], v[234:235], 2, s[4:5]
	global_load_dwordx4 v[218:221], v[234:235], off offset:16
	global_load_dwordx4 v[222:225], v[234:235], off
	global_load_dwordx4 v[226:229], v[138:139], off offset:528
	global_load_dwordx4 v[230:233], v[138:139], off offset:512
	s_mov_b32 s17, 0x100000
	s_mov_b64 s[44:45], 0x100000
	v_readlane_b32 s37, v254, 63
	s_waitcnt vmcnt(4)
	v_pk_fma_f32 v[122:123], v[122:123], v[194:195], v[202:203]
	v_pk_fma_f32 v[120:121], v[120:121], v[192:193], v[200:201]
	global_store_dwordx4 v[138:139], v[120:123], off offset:16
	v_pk_fma_f32 v[126:127], v[126:127], v[198:199], v[216:217]
	v_pk_fma_f32 v[124:125], v[124:125], v[196:197], v[214:215]
	v_or_b32_e32 v120, 0x80, v158
	v_ashrrev_i32_e32 v121, 31, v120
	global_store_dwordx4 v[138:139], v[124:127], off
	v_lshl_add_u64 v[120:121], v[120:121], 2, s[4:5]
	global_load_dwordx4 v[192:195], v[140:141], off offset:16
	global_load_dwordx4 v[196:199], v[140:141], off
	v_or_b32_e32 v234, 16, v144
	v_ashrrev_i32_e32 v235, 31, v234
	v_lshlrev_b64 v[234:235], 13, v[234:235]
	v_lshl_add_u64 v[234:235], s[6:7], 0, v[234:235]
	v_lshl_add_u64 v[236:237], v[234:235], 0, v[142:143]
	global_load_dwordx4 v[200:203], v[236:237], off offset:16
	global_load_dwordx4 v[214:217], v[236:237], off
	s_waitcnt vmcnt(6)
	v_pk_fma_f32 v[112:113], v[112:113], v[218:219], v[226:227]
	v_or_b32_e32 v122, 16, v144
	v_ashrrev_i32_e32 v123, 31, v122
	v_lshlrev_b64 v[122:123], 13, v[122:123]
	v_pk_fma_f32 v[118:119], v[118:119], v[224:225], v[232:233]
	v_pk_fma_f32 v[116:117], v[116:117], v[222:223], v[230:231]
	v_pk_fma_f32 v[114:115], v[114:115], v[220:221], v[228:229]
	v_lshl_add_u64 v[122:123], s[6:7], 0, v[122:123]
	global_store_dwordx4 v[138:139], v[116:119], off offset:512
	global_store_dwordx4 v[138:139], v[112:115], off offset:528
	v_lshl_add_u64 v[126:127], v[122:123], 0, v[142:143]
	v_or_b32_e32 v234, 0x80, v158
	v_ashrrev_i32_e32 v235, 31, v234
	v_lshl_add_u64 v[234:235], v[234:235], 2, s[4:5]
	global_load_dwordx4 v[218:221], v[234:235], off offset:16
	global_load_dwordx4 v[222:225], v[234:235], off
	v_or_b32_e32 v234, 16, v144
	v_ashrrev_i32_e32 v235, 31, v234
	v_lshlrev_b64 v[234:235], 13, v[234:235]
	v_lshl_add_u64 v[234:235], s[6:7], 0, v[234:235]
	v_lshl_add_u64 v[236:237], v[234:235], 0, v[142:143]
	global_load_dwordx4 v[226:229], v[236:237], off offset:528
	global_load_dwordx4 v[230:233], v[236:237], off offset:512
	s_waitcnt vmcnt(6)
	v_pk_fma_f32 v[106:107], v[106:107], v[194:195], v[202:203]
	v_pk_fma_f32 v[110:111], v[110:111], v[198:199], v[216:217]
	v_pk_fma_f32 v[108:109], v[108:109], v[196:197], v[214:215]
	v_pk_fma_f32 v[104:105], v[104:105], v[192:193], v[200:201]
	global_store_dwordx4 v[126:127], v[108:111], off
	global_store_dwordx4 v[126:127], v[104:107], off offset:16
	global_load_dwordx4 v[192:195], v[140:141], off offset:16
	global_load_dwordx4 v[196:199], v[140:141], off
	v_or_b32_e32 v234, 32, v144
	v_ashrrev_i32_e32 v235, 31, v234
	v_lshlrev_b64 v[234:235], 13, v[234:235]
	v_lshl_add_u64 v[234:235], s[6:7], 0, v[234:235]
	v_lshl_add_u64 v[236:237], v[234:235], 0, v[142:143]
	global_load_dwordx4 v[200:203], v[236:237], off offset:16
	global_load_dwordx4 v[214:217], v[236:237], off
	s_nop 0
	s_waitcnt vmcnt(6)
	v_pk_fma_f32 v[96:97], v[96:97], v[218:219], v[226:227]
	v_or_b32_e32 v104, 32, v144
	v_ashrrev_i32_e32 v105, 31, v104
	v_lshlrev_b64 v[104:105], 13, v[104:105]
	v_pk_fma_f32 v[102:103], v[102:103], v[224:225], v[232:233]
	v_pk_fma_f32 v[100:101], v[100:101], v[222:223], v[230:231]
	v_pk_fma_f32 v[98:99], v[98:99], v[220:221], v[228:229]
	v_lshl_add_u64 v[104:105], s[6:7], 0, v[104:105]
	global_store_dwordx4 v[126:127], v[100:103], off offset:512
	global_store_dwordx4 v[126:127], v[96:99], off offset:528
	v_lshl_add_u64 v[112:113], v[104:105], 0, v[142:143]
	v_or_b32_e32 v234, 0x80, v158
	v_ashrrev_i32_e32 v235, 31, v234
	v_lshl_add_u64 v[234:235], v[234:235], 2, s[4:5]
	global_load_dwordx4 v[218:221], v[234:235], off offset:16
	global_load_dwordx4 v[222:225], v[234:235], off
	v_or_b32_e32 v234, 32, v144
	v_ashrrev_i32_e32 v235, 31, v234
	v_lshlrev_b64 v[234:235], 13, v[234:235]
	v_lshl_add_u64 v[234:235], s[6:7], 0, v[234:235]
	v_lshl_add_u64 v[236:237], v[234:235], 0, v[142:143]
	global_load_dwordx4 v[226:229], v[236:237], off offset:528
	global_load_dwordx4 v[230:233], v[236:237], off offset:512
	s_waitcnt vmcnt(6)
	v_pk_fma_f32 v[90:91], v[90:91], v[194:195], v[202:203]
	v_pk_fma_f32 v[94:95], v[94:95], v[198:199], v[216:217]
	v_pk_fma_f32 v[92:93], v[92:93], v[196:197], v[214:215]
	v_pk_fma_f32 v[88:89], v[88:89], v[192:193], v[200:201]
	global_store_dwordx4 v[112:113], v[92:95], off
	global_store_dwordx4 v[112:113], v[88:91], off offset:16
	global_load_dwordx4 v[192:195], v[140:141], off offset:16
	global_load_dwordx4 v[196:199], v[140:141], off
	v_or_b32_e32 v234, 48, v144
	v_ashrrev_i32_e32 v235, 31, v234
	v_lshlrev_b64 v[234:235], 13, v[234:235]
	v_lshl_add_u64 v[234:235], s[6:7], 0, v[234:235]
	v_lshl_add_u64 v[236:237], v[234:235], 0, v[142:143]
	global_load_dwordx4 v[200:203], v[236:237], off offset:16
	global_load_dwordx4 v[214:217], v[236:237], off
	s_nop 0
	s_waitcnt vmcnt(6)
;     __device__ __forceinline__ void operator()(const f32x4 (&acc)[2][2][4][2], const pg8::Unit& u, int wr, int wc, int fr, int fq) const {
;     ...
;         for (int ai = 0; ai < 2; ++ai)
; #pragma unroll
;             for (int m = 0; m < 4; ++m) {
;                 const size_t row = (size_t)(row0 + ai * 128 + m * 16);
;                 float ssq = 0.f, rstd = 1.f;
;                 if constexpr (MODE == 8) rstd = 1.f / sqrtf(rs[row] * (1.f / DM) + EPS);
; #pragma unroll
;                 for (int bj = 0; bj < 2; ++bj) {
;                     const int col = col0 + bj * 128;
;                     f32x4 v0 = acc[ai][bj][m][0], v1 = acc[ai][bj][m][1];
;     ...
;                     } else if constexpr (MODE == 4) {
;                         const f32x4 g0 = *(const f32x4*)(vec + col), g1 = *(const f32x4*)(vec + col + 4);
;                         const f32x4 x0 = *(const f32x4*)(xsrc + row * DM + col), x1 = *(const f32x4*)(xsrc + row * DM + col + 4);
;                         *(f32x4*)(of + row * DM + col) = x0 + g0 * v0; *(f32x4*)(of + row * DM + col + 4) = x1 + g1 * v1;
	v_pk_fma_f32 v[80:81], v[80:81], v[218:219], v[226:227]
	v_or_b32_e32 v88, 48, v144
	v_ashrrev_i32_e32 v89, 31, v88
	v_lshlrev_b64 v[88:89], 13, v[88:89]
	v_pk_fma_f32 v[86:87], v[86:87], v[224:225], v[232:233]
	v_pk_fma_f32 v[84:85], v[84:85], v[222:223], v[230:231]
	v_pk_fma_f32 v[82:83], v[82:83], v[220:221], v[228:229]
	v_lshl_add_u64 v[88:89], s[6:7], 0, v[88:89]
	global_store_dwordx4 v[112:113], v[84:87], off offset:512
	global_store_dwordx4 v[112:113], v[80:83], off offset:528
	v_lshl_add_u64 v[96:97], v[88:89], 0, v[142:143]
	v_or_b32_e32 v234, 0x80, v158
	v_ashrrev_i32_e32 v235, 31, v234
	v_lshl_add_u64 v[234:235], v[234:235], 2, s[4:5]
	global_load_dwordx4 v[218:221], v[234:235], off offset:16
	global_load_dwordx4 v[222:225], v[234:235], off
	v_or_b32_e32 v234, 48, v144
	v_ashrrev_i32_e32 v235, 31, v234
	v_lshlrev_b64 v[234:235], 13, v[234:235]
	v_lshl_add_u64 v[234:235], s[6:7], 0, v[234:235]
	v_lshl_add_u64 v[236:237], v[234:235], 0, v[142:143]
	global_load_dwordx4 v[226:229], v[236:237], off offset:528
	global_load_dwordx4 v[230:233], v[236:237], off offset:512
	s_waitcnt vmcnt(6)
	v_pk_fma_f32 v[74:75], v[74:75], v[194:195], v[202:203]
	v_pk_fma_f32 v[78:79], v[78:79], v[198:199], v[216:217]
	v_pk_fma_f32 v[76:77], v[76:77], v[196:197], v[214:215]
	v_pk_fma_f32 v[72:73], v[72:73], v[192:193], v[200:201]
	global_store_dwordx4 v[96:97], v[76:79], off
	global_store_dwordx4 v[96:97], v[72:75], off offset:16
	global_load_dwordx4 v[192:195], v[140:141], off offset:16
	global_load_dwordx4 v[196:199], v[140:141], off
	s_mov_b32 s98, 0x100000
	v_add_co_u32_e32 v234, vcc, s98, v138
	s_nop 1
	v_addc_co_u32_e32 v235, vcc, 0, v139, vcc
	global_load_dwordx4 v[200:203], v[234:235], off
	s_mov_b64 s[98:99], 0x100000
	v_lshl_add_u64 v[234:235], v[138:139], 0, s[98:99]
	global_load_dwordx4 v[214:217], v[234:235], off offset:16
	s_nop 0
	s_waitcnt vmcnt(6)
	v_pk_fma_f32 v[66:67], v[66:67], v[220:221], v[228:229]
	v_pk_fma_f32 v[70:71], v[70:71], v[224:225], v[232:233]
	v_pk_fma_f32 v[68:69], v[68:69], v[222:223], v[230:231]
	v_pk_fma_f32 v[64:65], v[64:65], v[218:219], v[226:227]
	v_add_co_u32_e32 v82, vcc, s17, v138
	global_store_dwordx4 v[96:97], v[68:71], off offset:512
	global_store_dwordx4 v[96:97], v[64:67], off offset:528
	v_addc_co_u32_e32 v83, vcc, 0, v139, vcc
	v_or_b32_e32 v234, 0x80, v158
	v_ashrrev_i32_e32 v235, 31, v234
	v_lshl_add_u64 v[234:235], v[234:235], 2, s[4:5]
	global_load_dwordx4 v[218:221], v[234:235], off offset:16
	global_load_dwordx4 v[222:225], v[234:235], off
	s_mov_b64 s[98:99], 0x100000
	v_lshl_add_u64 v[234:235], v[138:139], 0, s[98:99]
	global_load_dwordx4 v[226:229], v[234:235], off offset:528
	s_mov_b64 s[98:99], 0x100000
	global_load_dwordx4 v[230:233], v[234:235], off offset:512
	v_lshl_add_u64 v[80:81], v[138:139], 0, s[44:45]
	s_mov_b32 s17, 0x120000
	s_mov_b64 s[44:45], 0x120000
	s_waitcnt vmcnt(6)
	v_pk_fma_f32 v[62:63], v[62:63], v[198:199], v[202:203]
	v_pk_fma_f32 v[60:61], v[60:61], v[196:197], v[200:201]
	v_pk_fma_f32 v[58:59], v[58:59], v[194:195], v[216:217]
	v_pk_fma_f32 v[56:57], v[56:57], v[192:193], v[214:215]
	global_store_dwordx4 v[82:83], v[60:63], off
	global_store_dwordx4 v[80:81], v[56:59], off offset:16
	global_load_dwordx4 v[192:195], v[140:141], off offset:16
	global_load_dwordx4 v[196:199], v[140:141], off
	s_mov_b32 s98, 0x120000
	v_add_co_u32_e32 v234, vcc, s98, v138
	s_nop 1
	v_addc_co_u32_e32 v235, vcc, 0, v139, vcc
	global_load_dwordx4 v[200:203], v[234:235], off
	s_mov_b64 s[98:99], 0x120000
	v_lshl_add_u64 v[234:235], v[138:139], 0, s[98:99]
	global_load_dwordx4 v[214:217], v[234:235], off offset:16
	s_nop 0
	s_waitcnt vmcnt(6)
	v_pk_fma_f32 v[50:51], v[50:51], v[220:221], v[228:229]
	v_pk_fma_f32 v[54:55], v[54:55], v[224:225], v[232:233]
	v_pk_fma_f32 v[52:53], v[52:53], v[222:223], v[230:231]
	v_pk_fma_f32 v[48:49], v[48:49], v[218:219], v[226:227]
	v_add_co_u32_e32 v66, vcc, s17, v138
	global_store_dwordx4 v[80:81], v[52:55], off offset:512
	global_store_dwordx4 v[80:81], v[48:51], off offset:528
	v_addc_co_u32_e32 v67, vcc, 0, v139, vcc
	v_or_b32_e32 v234, 0x80, v158
	v_ashrrev_i32_e32 v235, 31, v234
	v_lshl_add_u64 v[234:235], v[234:235], 2, s[4:5]
	global_load_dwordx4 v[218:221], v[234:235], off offset:16
	global_load_dwordx4 v[222:225], v[234:235], off
	s_mov_b64 s[98:99], 0x120000
	v_lshl_add_u64 v[234:235], v[138:139], 0, s[98:99]
	global_load_dwordx4 v[226:229], v[234:235], off offset:528
	s_mov_b64 s[98:99], 0x120000
	global_load_dwordx4 v[230:233], v[234:235], off offset:512
	v_lshl_add_u64 v[64:65], v[138:139], 0, s[44:45]
	s_mov_b32 s17, 0x140000
	s_mov_b64 s[44:45], 0x140000
	s_waitcnt vmcnt(6)
;     __device__ __forceinline__ void operator()(const f32x4 (&acc)[2][2][4][2], const pg8::Unit& u, int wr, int wc, int fr, int fq) const {
;     ...
;         for (int ai = 0; ai < 2; ++ai)
; #pragma unroll
;             for (int m = 0; m < 4; ++m) {
;                 const size_t row = (size_t)(row0 + ai * 128 + m * 16);
;                 float ssq = 0.f, rstd = 1.f;
;                 if constexpr (MODE == 8) rstd = 1.f / sqrtf(rs[row] * (1.f / DM) + EPS);
; #pragma unroll
;                 for (int bj = 0; bj < 2; ++bj) {
;                     const int col = col0 + bj * 128;
;                     f32x4 v0 = acc[ai][bj][m][0], v1 = acc[ai][bj][m][1];
;     ...
;                     } else if constexpr (MODE == 4) {
;                         const f32x4 g0 = *(const f32x4*)(vec + col), g1 = *(const f32x4*)(vec + col + 4);
;                         const f32x4 x0 = *(const f32x4*)(xsrc + row * DM + col), x1 = *(const f32x4*)(xsrc + row * DM + col + 4);
;                         *(f32x4*)(of + row * DM + col) = x0 + g0 * v0; *(f32x4*)(of + row * DM + col + 4) = x1 + g1 * v1;
	v_pk_fma_f32 v[46:47], v[46:47], v[198:199], v[202:203]
	v_pk_fma_f32 v[44:45], v[44:45], v[196:197], v[200:201]
	v_pk_fma_f32 v[42:43], v[42:43], v[194:195], v[216:217]
	v_pk_fma_f32 v[40:41], v[40:41], v[192:193], v[214:215]
	global_store_dwordx4 v[66:67], v[44:47], off
	global_store_dwordx4 v[64:65], v[40:43], off offset:16
	global_load_dwordx4 v[192:195], v[140:141], off offset:16
	global_load_dwordx4 v[196:199], v[140:141], off
	s_mov_b32 s98, 0x140000
	v_add_co_u32_e32 v234, vcc, s98, v138
	s_nop 1
	v_addc_co_u32_e32 v235, vcc, 0, v139, vcc
	global_load_dwordx4 v[200:203], v[234:235], off
	s_mov_b64 s[98:99], 0x140000
	v_lshl_add_u64 v[234:235], v[138:139], 0, s[98:99]
	global_load_dwordx4 v[214:217], v[234:235], off offset:16
	s_nop 0
	s_waitcnt vmcnt(6)
	v_pk_fma_f32 v[34:35], v[34:35], v[220:221], v[228:229]
	v_pk_fma_f32 v[38:39], v[38:39], v[224:225], v[232:233]
	v_pk_fma_f32 v[36:37], v[36:37], v[222:223], v[230:231]
	v_pk_fma_f32 v[32:33], v[32:33], v[218:219], v[226:227]
	v_add_co_u32_e32 v50, vcc, s17, v138
	global_store_dwordx4 v[64:65], v[36:39], off offset:512
	global_store_dwordx4 v[64:65], v[32:35], off offset:528
	v_addc_co_u32_e32 v51, vcc, 0, v139, vcc
	v_or_b32_e32 v234, 0x80, v158
	v_ashrrev_i32_e32 v235, 31, v234
	v_lshl_add_u64 v[234:235], v[234:235], 2, s[4:5]
	global_load_dwordx4 v[218:221], v[234:235], off offset:16
	global_load_dwordx4 v[222:225], v[234:235], off
	s_mov_b64 s[98:99], 0x140000
	v_lshl_add_u64 v[234:235], v[138:139], 0, s[98:99]
	global_load_dwordx4 v[226:229], v[234:235], off offset:528
	s_mov_b64 s[98:99], 0x140000
	global_load_dwordx4 v[230:233], v[234:235], off offset:512
	v_lshl_add_u64 v[48:49], v[138:139], 0, s[44:45]
	s_mov_b32 s17, 0x160000
	s_mov_b64 s[44:45], 0x160000
	s_waitcnt vmcnt(6)
	v_pk_fma_f32 v[30:31], v[30:31], v[198:199], v[202:203]
	v_pk_fma_f32 v[28:29], v[28:29], v[196:197], v[200:201]
	v_pk_fma_f32 v[26:27], v[26:27], v[194:195], v[216:217]
	v_pk_fma_f32 v[24:25], v[24:25], v[192:193], v[214:215]
	global_store_dwordx4 v[50:51], v[28:31], off
	global_store_dwordx4 v[48:49], v[24:27], off offset:16
	global_load_dwordx4 v[192:195], v[140:141], off offset:16
	global_load_dwordx4 v[196:199], v[140:141], off
	s_mov_b32 s98, 0x160000
	v_add_co_u32_e32 v234, vcc, s98, v138
	s_nop 1
	v_addc_co_u32_e32 v235, vcc, 0, v139, vcc
	global_load_dwordx4 v[200:203], v[234:235], off
	s_mov_b64 s[98:99], 0x160000
	v_lshl_add_u64 v[234:235], v[138:139], 0, s[98:99]
	global_load_dwordx4 v[214:217], v[234:235], off offset:16
	s_nop 0
	s_waitcnt vmcnt(6)
	v_pk_fma_f32 v[18:19], v[18:19], v[220:221], v[228:229]
	v_pk_fma_f32 v[22:23], v[22:23], v[224:225], v[232:233]
	v_pk_fma_f32 v[20:21], v[20:21], v[222:223], v[230:231]
	v_pk_fma_f32 v[16:17], v[16:17], v[218:219], v[226:227]
	v_add_co_u32_e32 v34, vcc, s17, v138
	global_store_dwordx4 v[48:49], v[20:23], off offset:512
	global_store_dwordx4 v[48:49], v[16:19], off offset:528
	v_addc_co_u32_e32 v35, vcc, 0, v139, vcc
	v_or_b32_e32 v234, 0x80, v158
	v_ashrrev_i32_e32 v235, 31, v234
	v_lshl_add_u64 v[234:235], v[234:235], 2, s[4:5]
	global_load_dwordx4 v[218:221], v[234:235], off offset:16
	global_load_dwordx4 v[222:225], v[234:235], off
	s_mov_b64 s[98:99], 0x160000
	v_lshl_add_u64 v[234:235], v[138:139], 0, s[98:99]
	global_load_dwordx4 v[226:229], v[234:235], off offset:528
	s_mov_b64 s[98:99], 0x160000
	global_load_dwordx4 v[230:233], v[234:235], off offset:512
	v_lshl_add_u64 v[32:33], v[138:139], 0, s[44:45]
	s_mov_b64 s[44:45], -1
	s_andn2_b64 vcc, exec, s[38:39]
	s_waitcnt vmcnt(6)
	v_pk_fma_f32 v[14:15], v[14:15], v[198:199], v[202:203]
	v_pk_fma_f32 v[12:13], v[12:13], v[196:197], v[200:201]
	v_pk_fma_f32 v[10:11], v[10:11], v[194:195], v[216:217]
	v_pk_fma_f32 v[8:9], v[8:9], v[192:193], v[214:215]
	global_store_dwordx4 v[34:35], v[12:15], off
	global_store_dwordx4 v[32:33], v[8:11], off offset:16
	s_nop 0
	s_waitcnt vmcnt(2)
	v_pk_fma_f32 v[2:3], v[2:3], v[220:221], v[228:229]
	v_pk_fma_f32 v[6:7], v[6:7], v[224:225], v[232:233]
	v_pk_fma_f32 v[4:5], v[4:5], v[222:223], v[230:231]
	v_pk_fma_f32 v[0:1], v[0:1], v[218:219], v[226:227]
	global_store_dwordx4 v[32:33], v[4:7], off offset:512
	global_store_dwordx4 v[32:33], v[0:3], off offset:528
	s_cbranch_vccnz .LBB0_1140
	s_andn2_b64 vcc, exec, s[0:1]
	s_cbranch_vccnz .LBB0_1139
	s_barrier
	s_branch .LBB0_1139
